# static s_setprio 1 for waves 4-7 across the SwiGLU GEMM K loop instead of per-phase priority flips
# speedup vs baseline: 1.0063x; 1.0038x over previous
; #define WAIT_V(n) asm volatile("s_waitcnt vmcnt(" #n ")" ::: "memory")
; #define BAR __builtin_amdgcn_s_barrier()
;   DI const float* prefetch_base(int brow, int bcol) const { return (brow < M_LAT ? hin_lat : hin_ctx - (size_t)M_LAT * DM) + (size_t)brow * DM + bcol; }
; template <int K, bool HALFM, class Epi>
; DI void gemm_tile(unsigned char* lds, const int tid, const u16* __restrict__ A, const u16* __restrict__ Bt, int brow, int bcol, Epi& epi,
;                   const bool prefetched, const bool has_next, const int nbrow, const int nbcol) {
;     ...
;   const int tid16 = tid * 16;
;   const unsigned ldsw = (unsigned)__builtin_amdgcn_readfirstlane((int)(((unsigned)(size_t)lds) + (unsigned)(tid >> 6) * 1024u));
;   unsigned voff0, voff1;
;   { int r_, c_; stage_rc(tid16, r_, c_); voff0 = (unsigned)(r_ * K + c_) * 2u;
;     stage_rc(tid16 + 8192, r_, c_); voff1 = (unsigned)(r_ * K + c_) * 2u; }
;   const int wid = tid >> 6, lane = tid & 63, wr = wid >> 2, wc = wid & 3, fr = lane & 15, fq = lane >> 4;
;   f32x4 acc[2][2][4][2];
; #pragma unroll
;   for (int a = 0; a < 2; ++a)
; #pragma unroll
;     for (int b = 0; b < 2; ++b)
; #pragma unroll
;       for (int m = 0; m < 4; ++m)
; #pragma unroll
;         for (int n = 0; n < 2; ++n) acc[a][b][m][n] = (f32x4){0.f, 0.f, 0.f, 0.f};
;   bf16x8 At[4][2], B0[2][2], B1[2][2];
;   const int nt = K / 64;
;   {
;     const char* pfb = (const char*)epi.prefetch_base(brow, bcol);
;     if (pfb) {
;       const unsigned pm0 = (unsigned)__builtin_amdgcn_readfirstlane((int)((unsigned)(size_t)lds + LDS_PF));
; #pragma unroll
;       for (int i = 0; i < 4; ++i) {
;         const int li = tid + i * 512;
;         const unsigned vo = (unsigned)((li >> 3) * DM * 4 + (li & 7) * 128);
;         asm volatile("s_mov_b32 m0, %0\n\ts_nop 0\n\tglobal_load_lds_dword %1, %2" :: "s"(pm0), "v"(vo), "s"(pfb) : "m0", "memory");
;       }
;     }
;   }
;   const float4 pre_v = epi.pre_load(tid, brow);
;   if (!prefetched) {
;     STAGE(SB(0, 0), Bt, bcol, 0); STAGE(SA(0, 0), A, brow, 0);
;     STAGE(SB(0, 1), Bt, bcol + HALF, 0); STAGE(SA(0, 1), A, brow + AH, 0);
;   }
;   if (wr == 1) BAR;
;   if (!prefetched) WAIT_V(4);
;   BAR;
;   epi.pre_use(pre_v, tid, lds);
;   if (!prefetched) {
;     STAGE(SB(1, 0), Bt, bcol, 1); STAGE(SA(1, 0), A, brow, 1); STAGE(SB(1, 1), Bt, bcol + HALF, 1);
;     WAIT_V(6);
;   }
;   BAR;
.LBB0_995:
	s_waitcnt vmcnt(0) lgkmcnt(0)
	v_and_b32_e32 v2, 15, v138
	v_lshlrev_b32_e32 v5, 2, v138
	v_and_b32_e32 v3, 48, v138
	v_lshlrev_b32_e32 v2, 6, v2
	v_and_b32_e32 v5, 32, v5
	s_add_i32 s3, 0, 0x10000
	v_bitop3_b32 v2, v2, v5, v3 bitop3:0x36
	s_cmp_lg_u32 0, -1
	v_lshlrev_b32_e32 v4, 12, v6
	v_add_u32_e32 v6, s3, v2
	s_cselect_b32 s3, 0, 0
	s_add_i32 s14, s3, s5
	s_add_i32 s3, 0, 0x14000
	v_add_u32_e32 v8, s3, v2
	s_add_i32 s3, 0, 0x18000
	s_add_i32 s55, 0, 0x1c000
	s_add_i32 s7, s14, 0xc000
	s_add_i32 s54, s14, 0xe000
	s_add_i32 s5, s14, 0x10000
	s_add_i32 s53, s14, 0x12000
	s_add_i32 s52, s14, 0x2000
	s_add_i32 s15, s14, 0x14000
	s_add_i32 s51, s14, 0x16000
	v_add_u32_e32 v9, s3, v2
	s_add_i32 s3, s14, 0x4000
	s_addk_i32 s14, 0x6000
	v_add_u32_e32 v10, s55, v2
	v_add_u32_e32 v11, 0, v2
	v_lshlrev_b32_e32 v2, 6, v138
	s_movk_i32 s55, 0x3c0
	v_readlane_b32 s58, v254, 59
	v_and_or_b32 v2, v2, s55, v3
	v_readlane_b32 s59, v254, 60
	s_add_u32 s55, s58, s10
	s_addc_u32 s56, s59, s11
	s_add_u32 s12, s18, s12
	s_addc_u32 s13, s19, s13
	s_add_u32 s10, s58, s10
	v_lshlrev_b32_e32 v7, 13, v7
	s_addc_u32 s11, s59, s11
	v_and_b32_e32 v4, 0x3000, v4
	v_xad_u32 v3, v2, v5, 0
	v_or_b32_e32 v5, 0x800, v7
	v_or_b32_e32 v12, 0x1000, v7
	v_or_b32_e32 v13, 0x1800, v7
	s_add_u32 s57, s18, s0
	v_mov_b32_e32 v2, 0
	s_addc_u32 s58, s19, s1
	s_mov_b32 s59, -2
	s_mov_b64 s[0:1], 0
	v_add_u32_e32 v132, v6, v4
	v_add_u32_e32 v143, v11, v7
	v_add_u32_e32 v142, v3, v5
	v_add_u32_e32 v141, v3, v12
	v_add_u32_e32 v140, v3, v13
	v_add_u32_e32 v131, v8, v4
	v_add_u32_e32 v130, v9, v4
	v_add_u32_e32 v134, v10, v4
	v_mov_b32_e32 v3, v2
	v_mov_b32_e32 v4, v2
	v_mov_b32_e32 v5, v2
	v_mov_b32_e32 v6, v2
	v_mov_b32_e32 v7, v2
	v_mov_b32_e32 v8, v2
	v_mov_b32_e32 v9, v2
	v_mov_b32_e32 v10, v2
	v_mov_b32_e32 v11, v2
	v_mov_b32_e32 v12, v2
	v_mov_b32_e32 v13, v2
	v_mov_b32_e32 v14, v2
	v_mov_b32_e32 v15, v2
	v_mov_b32_e32 v16, v2
	v_mov_b32_e32 v17, v2
	v_mov_b32_e32 v18, v2
	v_mov_b32_e32 v19, v2
	v_mov_b32_e32 v20, v2
	v_mov_b32_e32 v21, v2
	v_mov_b32_e32 v22, v2
	v_mov_b32_e32 v23, v2
	v_mov_b32_e32 v24, v2
	v_mov_b32_e32 v25, v2
	v_mov_b32_e32 v26, v2
	v_mov_b32_e32 v27, v2
	v_mov_b32_e32 v28, v2
	v_mov_b32_e32 v29, v2
	v_mov_b32_e32 v30, v2
	v_mov_b32_e32 v31, v2
	v_mov_b32_e32 v32, v2
	v_mov_b32_e32 v33, v2
	v_mov_b32_e32 v34, v2
	v_mov_b32_e32 v35, v2
	v_mov_b32_e32 v36, v2
	v_mov_b32_e32 v37, v2
	v_mov_b32_e32 v38, v2
	v_mov_b32_e32 v39, v2
	v_mov_b32_e32 v40, v2
	v_mov_b32_e32 v41, v2
	v_mov_b32_e32 v42, v2
	v_mov_b32_e32 v43, v2
	v_mov_b32_e32 v44, v2
	v_mov_b32_e32 v45, v2
	v_mov_b32_e32 v46, v2
	v_mov_b32_e32 v47, v2
	v_mov_b32_e32 v48, v2
	v_mov_b32_e32 v49, v2
	v_mov_b32_e32 v50, v2
	v_mov_b32_e32 v51, v2
	v_mov_b32_e32 v52, v2
	v_mov_b32_e32 v53, v2
	v_mov_b32_e32 v54, v2
	v_mov_b32_e32 v55, v2
	v_mov_b32_e32 v56, v2
	v_mov_b32_e32 v57, v2
	v_mov_b32_e32 v58, v2
	v_mov_b32_e32 v59, v2
	v_mov_b32_e32 v60, v2
	v_mov_b32_e32 v61, v2
	v_mov_b32_e32 v62, v2
	v_mov_b32_e32 v63, v2
	v_mov_b32_e32 v64, v2
	v_mov_b32_e32 v65, v2
	v_mov_b32_e32 v66, v2
	v_mov_b32_e32 v67, v2
	v_mov_b32_e32 v68, v2
	v_mov_b32_e32 v69, v2
	v_mov_b32_e32 v70, v2
	v_mov_b32_e32 v71, v2
	v_mov_b32_e32 v72, v2
	v_mov_b32_e32 v73, v2
	v_mov_b32_e32 v74, v2
	v_mov_b32_e32 v75, v2
	v_mov_b32_e32 v76, v2
	v_mov_b32_e32 v77, v2
	v_mov_b32_e32 v78, v2
	v_mov_b32_e32 v79, v2
	v_mov_b32_e32 v80, v2
	v_mov_b32_e32 v81, v2
	v_mov_b32_e32 v82, v2
	v_mov_b32_e32 v83, v2
	v_mov_b32_e32 v84, v2
	v_mov_b32_e32 v85, v2
	v_mov_b32_e32 v86, v2
	v_mov_b32_e32 v87, v2
	v_mov_b32_e32 v88, v2
	v_mov_b32_e32 v89, v2
	v_mov_b32_e32 v90, v2
	v_mov_b32_e32 v91, v2
	v_mov_b32_e32 v92, v2
	v_mov_b32_e32 v93, v2
	v_mov_b32_e32 v94, v2
	v_mov_b32_e32 v95, v2
	v_mov_b32_e32 v96, v2
	v_mov_b32_e32 v97, v2
	v_mov_b32_e32 v98, v2
	v_mov_b32_e32 v99, v2
	v_mov_b32_e32 v100, v2
	v_mov_b32_e32 v101, v2
	v_mov_b32_e32 v102, v2
	v_mov_b32_e32 v103, v2
	v_mov_b32_e32 v104, v2
	v_mov_b32_e32 v105, v2
	v_mov_b32_e32 v106, v2
	v_mov_b32_e32 v107, v2
	v_mov_b32_e32 v108, v2
	v_mov_b32_e32 v109, v2
	v_mov_b32_e32 v110, v2
	v_mov_b32_e32 v111, v2
	v_mov_b32_e32 v112, v2
	v_mov_b32_e32 v113, v2
	v_mov_b32_e32 v114, v2
	v_mov_b32_e32 v115, v2
	v_mov_b32_e32 v116, v2
	v_mov_b32_e32 v117, v2
	v_mov_b32_e32 v118, v2
	v_mov_b32_e32 v119, v2
	v_mov_b32_e32 v120, v2
	v_mov_b32_e32 v121, v2
	v_mov_b32_e32 v122, v2
	v_mov_b32_e32 v123, v2
	v_mov_b32_e32 v124, v2
	v_mov_b32_e32 v125, v2
	v_mov_b32_e32 v126, v2
	v_mov_b32_e32 v127, v2
	v_mov_b32_e32 v128, v2
	v_mov_b32_e32 v129, v2
	s_barrier
	s_cmpk_ge_u32 s90, 0x100
	s_cbranch_scc0 .Lprio_skip
	s_setprio 1
; #define LDA(dst, b, h) for (int m = 0; m < 4; ++m) for (int k = 0; k < 2; ++k) \
;     dst[m][k] = *reinterpret_cast<const bf16x8*>((char*)SA(b, h) + lds_byte(wr * 64 + m * 16 + fr, k * 32 + fq * 8))
; #define LDB(dst, b, h) for (int n = 0; n < 2; ++n) for (int k = 0; k < 2; ++k) \
;     dst[n][k] = *reinterpret_cast<const bf16x8*>((char*)SB(b, h) + lds_byte(wc * 32 + n * 16 + fr, k * 32 + fq * 8))
; #define MMA(ai, bj, At_, Bt_) do { __builtin_amdgcn_s_setprio(1); \
;     for (int m = 0; m < 4; ++m) for (int n = 0; n < 2; ++n) for (int k = 0; k < 2; ++k) \
;       acc[ai][bj][m][n] = __builtin_amdgcn_mfma_f32_16x16x32_bf16(Bt_[n][k], At_[m][k], acc[ai][bj][m][n], 0, 0, 0); \
;     __builtin_amdgcn_s_setprio(0); } while (0)
; #define MMA_H(ai, bj, At_, Bt_) do { if (!HALFM) MMA(ai, bj, At_, Bt_); } while (0)
; #define WAIT_L(n) asm volatile("s_waitcnt lgkmcnt(" #n ")" ::: "memory")
; #define BAR __builtin_amdgcn_s_barrier()
; #define SCHED __builtin_amdgcn_sched_barrier(0)
; template <int K, bool HALFM, class Epi>
; DI void gemm_tile(unsigned char* lds, const int tid, const u16* __restrict__ A, const u16* __restrict__ Bt, int brow, int bcol, Epi& epi,
;                   const bool prefetched, const bool has_next, const int nbrow, const int nbcol) {
;     ...
;   for (int t = 0; t < nt - 2; t += 2) {
;     LDB(B0, 0, 0); SCHED; LDA(At, 0, 0); STAGE(SA(1, 1), A, brow + AH, t + 1);
;     WAIT_L(8); BAR; WAIT_L(0); MMA(0, 0, At, B0); BAR; SCHED;
;     LDB(B1, 0, 1); STAGE(SB(0, 0), Bt, bcol, t + 2);
;     BAR; WAIT_L(0); MMA(0, 1, At, B1); BAR;
;     if (!HALFM) { LDA(At, 0, 1); } STAGE(SA(0, 0), A, brow, t + 2);
;     BAR; WAIT_L(0); MMA_H(1, 0, At, B0); BAR; SCHED;
;     STAGE(SB(0, 1), Bt, bcol + HALF, t + 2);
.Lprio_skip:
.LBB0_996:
	ds_read_b128 v[144:147], v132
	ds_read_b128 v[148:151], v132 offset:1024
	ds_read_b128 v[152:155], v132 offset:2048
	ds_read_b128 v[160:163], v132 offset:3072
	ds_read_b128 v[164:167], v143
	ds_read_b128 v[168:171], v143 offset:1024
	ds_read_b128 v[172:175], v142
	ds_read_b128 v[176:179], v142 offset:1024
	ds_read_b128 v[180:183], v141
	ds_read_b128 v[184:187], v141 offset:1024
	ds_read_b128 v[188:191], v140
	ds_read_b128 v[192:195], v140 offset:1024
	s_add_u32 s62, s55, s0
	s_addc_u32 s63, s56, s1
	s_add_u32 s60, s62, 0x40080
	s_addc_u32 s61, s63, 0
	s_mov_b32 m0, s7
	s_nop 0
	global_load_lds_dwordx4 v139, s[60:61]
	s_mov_b32 m0, s54
	s_nop 0
	global_load_lds_dwordx4 v0, s[60:61]
	s_waitcnt lgkmcnt(8)
	s_barrier
	s_waitcnt lgkmcnt(0)
	s_waitcnt lgkmcnt(7)
	v_mfma_f32_16x16x32_bf16 v[126:129], v[144:147], v[164:167], v[126:129]
	v_mfma_f32_16x16x32_bf16 v[122:125], v[152:155], v[164:167], v[122:125]
	s_waitcnt lgkmcnt(5)
	v_mfma_f32_16x16x32_bf16 v[118:121], v[144:147], v[172:175], v[118:121]
	v_mfma_f32_16x16x32_bf16 v[114:117], v[152:155], v[172:175], v[114:117]
	s_waitcnt lgkmcnt(3)
	v_mfma_f32_16x16x32_bf16 v[110:113], v[144:147], v[180:183], v[110:113]
	v_mfma_f32_16x16x32_bf16 v[106:109], v[152:155], v[180:183], v[106:109]
	s_waitcnt lgkmcnt(1)
	v_mfma_f32_16x16x32_bf16 v[102:105], v[144:147], v[188:191], v[102:105]
	v_mfma_f32_16x16x32_bf16 v[98:101], v[152:155], v[188:191], v[98:101]
	v_mfma_f32_16x16x32_bf16 v[126:129], v[148:151], v[168:171], v[126:129]
	v_mfma_f32_16x16x32_bf16 v[122:125], v[160:163], v[168:171], v[122:125]
	v_mfma_f32_16x16x32_bf16 v[118:121], v[148:151], v[176:179], v[118:121]
	v_mfma_f32_16x16x32_bf16 v[114:117], v[160:163], v[176:179], v[114:117]
	v_mfma_f32_16x16x32_bf16 v[110:113], v[148:151], v[184:187], v[110:113]
	v_mfma_f32_16x16x32_bf16 v[106:109], v[160:163], v[184:187], v[106:109]
	s_waitcnt lgkmcnt(0)
	v_mfma_f32_16x16x32_bf16 v[102:105], v[148:151], v[192:195], v[102:105]
	v_mfma_f32_16x16x32_bf16 v[98:101], v[160:163], v[192:195], v[98:101]
	s_barrier
	ds_read_b128 v[196:199], v131
	ds_read_b128 v[200:203], v131 offset:1024
	ds_read_b128 v[204:207], v131 offset:2048
	ds_read_b128 v[208:211], v131 offset:3072
	s_add_u32 s64, s57, s0
	s_addc_u32 s65, s58, s1
	s_add_u32 s60, s64, 0x100
	s_addc_u32 s61, s65, 0
	s_mov_b32 m0, s5
	s_nop 0
	global_load_lds_dwordx4 v139, s[60:61]
	s_mov_b32 m0, s53
	s_nop 0
	global_load_lds_dwordx4 v0, s[60:61]
	s_barrier
	s_waitcnt lgkmcnt(0)
	s_waitcnt lgkmcnt(3)
	v_mfma_f32_16x16x32_bf16 v[94:97], v[196:199], v[164:167], v[94:97]
	s_waitcnt lgkmcnt(1)
	v_mfma_f32_16x16x32_bf16 v[90:93], v[204:207], v[164:167], v[90:93]
	v_mfma_f32_16x16x32_bf16 v[86:89], v[196:199], v[172:175], v[86:89]
	v_mfma_f32_16x16x32_bf16 v[82:85], v[204:207], v[172:175], v[82:85]
	v_mfma_f32_16x16x32_bf16 v[78:81], v[196:199], v[180:183], v[78:81]
	v_mfma_f32_16x16x32_bf16 v[74:77], v[204:207], v[180:183], v[74:77]
	v_mfma_f32_16x16x32_bf16 v[70:73], v[196:199], v[188:191], v[70:73]
	v_mfma_f32_16x16x32_bf16 v[66:69], v[204:207], v[188:191], v[66:69]
	v_mfma_f32_16x16x32_bf16 v[94:97], v[200:203], v[168:171], v[94:97]
	s_waitcnt lgkmcnt(0)
	v_mfma_f32_16x16x32_bf16 v[90:93], v[208:211], v[168:171], v[90:93]
	v_mfma_f32_16x16x32_bf16 v[86:89], v[200:203], v[176:179], v[86:89]
	v_mfma_f32_16x16x32_bf16 v[82:85], v[208:211], v[176:179], v[82:85]
	v_mfma_f32_16x16x32_bf16 v[78:81], v[200:203], v[184:187], v[78:81]
	v_mfma_f32_16x16x32_bf16 v[74:77], v[208:211], v[184:187], v[74:77]
	v_mfma_f32_16x16x32_bf16 v[70:73], v[200:203], v[192:195], v[70:73]
	v_mfma_f32_16x16x32_bf16 v[66:69], v[208:211], v[192:195], v[66:69]
	s_barrier
	ds_read_b128 v[164:167], v143 offset:16384
	ds_read_b128 v[168:171], v143 offset:17408
	ds_read_b128 v[172:175], v142 offset:16384
	ds_read_b128 v[176:179], v142 offset:17408
	ds_read_b128 v[180:183], v141 offset:16384
	ds_read_b128 v[184:187], v141 offset:17408
	ds_read_b128 v[188:191], v140 offset:16384
	ds_read_b128 v[192:195], v140 offset:17408
	s_add_u32 s66, s10, s0
	s_addc_u32 s67, s11, s1
	s_add_u32 s60, s66, 0x100
	s_addc_u32 s61, s67, 0
	s_mov_b32 m0, s21
	s_nop 0
	global_load_lds_dwordx4 v139, s[60:61]
	s_mov_b32 m0, s52
	s_nop 0
	global_load_lds_dwordx4 v0, s[60:61]
	s_barrier
	s_waitcnt lgkmcnt(0)
	s_waitcnt lgkmcnt(7)
	v_mfma_f32_16x16x32_bf16 v[62:65], v[144:147], v[164:167], v[62:65]
	v_mfma_f32_16x16x32_bf16 v[58:61], v[152:155], v[164:167], v[58:61]
	s_waitcnt lgkmcnt(5)
	v_mfma_f32_16x16x32_bf16 v[54:57], v[144:147], v[172:175], v[54:57]
	v_mfma_f32_16x16x32_bf16 v[50:53], v[152:155], v[172:175], v[50:53]
	s_waitcnt lgkmcnt(3)
	v_mfma_f32_16x16x32_bf16 v[46:49], v[144:147], v[180:183], v[46:49]
	v_mfma_f32_16x16x32_bf16 v[42:45], v[152:155], v[180:183], v[42:45]
	s_waitcnt lgkmcnt(1)
	v_mfma_f32_16x16x32_bf16 v[38:41], v[144:147], v[188:191], v[38:41]
	v_mfma_f32_16x16x32_bf16 v[34:37], v[152:155], v[188:191], v[34:37]
	v_mfma_f32_16x16x32_bf16 v[62:65], v[148:151], v[168:171], v[62:65]
	v_mfma_f32_16x16x32_bf16 v[58:61], v[160:163], v[168:171], v[58:61]
	v_mfma_f32_16x16x32_bf16 v[54:57], v[148:151], v[176:179], v[54:57]
	v_mfma_f32_16x16x32_bf16 v[50:53], v[160:163], v[176:179], v[50:53]
	v_mfma_f32_16x16x32_bf16 v[46:49], v[148:151], v[184:187], v[46:49]
	v_mfma_f32_16x16x32_bf16 v[42:45], v[160:163], v[184:187], v[42:45]
	s_waitcnt lgkmcnt(0)
	v_mfma_f32_16x16x32_bf16 v[38:41], v[148:151], v[192:195], v[38:41]
	v_mfma_f32_16x16x32_bf16 v[34:37], v[160:163], v[192:195], v[34:37]
	s_barrier
	s_add_u32 s68, s12, s0
	s_addc_u32 s69, s13, s1
	s_add_u32 s60, s68, 0x100
	s_addc_u32 s61, s69, 0
	s_mov_b32 m0, s15
	s_nop 0
	global_load_lds_dwordx4 v139, s[60:61]
	s_mov_b32 m0, s51
	s_nop 0
	global_load_lds_dwordx4 v0, s[60:61]
	s_waitcnt vmcnt(6)
	s_barrier
; #define LDA(dst, b, h) for (int m = 0; m < 4; ++m) for (int k = 0; k < 2; ++k) \
;     dst[m][k] = *reinterpret_cast<const bf16x8*>((char*)SA(b, h) + lds_byte(wr * 64 + m * 16 + fr, k * 32 + fq * 8))
; #define LDB(dst, b, h) for (int n = 0; n < 2; ++n) for (int k = 0; k < 2; ++k) \
;     dst[n][k] = *reinterpret_cast<const bf16x8*>((char*)SB(b, h) + lds_byte(wc * 32 + n * 16 + fr, k * 32 + fq * 8))
; #define MMA(ai, bj, At_, Bt_) do { __builtin_amdgcn_s_setprio(1); \
;     for (int m = 0; m < 4; ++m) for (int n = 0; n < 2; ++n) for (int k = 0; k < 2; ++k) \
;       acc[ai][bj][m][n] = __builtin_amdgcn_mfma_f32_16x16x32_bf16(Bt_[n][k], At_[m][k], acc[ai][bj][m][n], 0, 0, 0); \
;     __builtin_amdgcn_s_setprio(0); } while (0)
; #define MMA_H(ai, bj, At_, Bt_) do { if (!HALFM) MMA(ai, bj, At_, Bt_); } while (0)
; #define WAIT_V(n) asm volatile("s_waitcnt vmcnt(" #n ")" ::: "memory")
; #define WAIT_L(n) asm volatile("s_waitcnt lgkmcnt(" #n ")" ::: "memory")
; #define BAR __builtin_amdgcn_s_barrier()
; #define SCHED __builtin_amdgcn_sched_barrier(0)
; template <int K, bool HALFM, class Epi>
; DI void gemm_tile(unsigned char* lds, const int tid, const u16* __restrict__ A, const u16* __restrict__ Bt, int brow, int bcol, Epi& epi,
;                   const bool prefetched, const bool has_next, const int nbrow, const int nbcol) {
;     ...
;     STAGE(SB(0, 1), Bt, bcol + HALF, t + 2);
;     WAIT_V(6); BAR; MMA_H(1, 1, At, B1); BAR;
;     LDB(B0, 1, 0); SCHED; LDA(At, 1, 0); STAGE(SA(0, 1), A, brow + AH, t + 2);
;     WAIT_L(8); BAR; WAIT_L(0); MMA(0, 0, At, B0); BAR; SCHED;
;     LDB(B1, 1, 1); STAGE(SB(1, 0), Bt, bcol, t + 3);
;     BAR; WAIT_L(0); MMA(0, 1, At, B1); BAR;
	v_mfma_f32_16x16x32_bf16 v[30:33], v[196:199], v[164:167], v[30:33]
	v_mfma_f32_16x16x32_bf16 v[26:29], v[204:207], v[164:167], v[26:29]
	v_mfma_f32_16x16x32_bf16 v[22:25], v[196:199], v[172:175], v[22:25]
	v_mfma_f32_16x16x32_bf16 v[18:21], v[204:207], v[172:175], v[18:21]
	v_mfma_f32_16x16x32_bf16 v[14:17], v[196:199], v[180:183], v[14:17]
	v_mfma_f32_16x16x32_bf16 v[10:13], v[204:207], v[180:183], v[10:13]
	v_mfma_f32_16x16x32_bf16 v[6:9], v[196:199], v[188:191], v[6:9]
	v_mfma_f32_16x16x32_bf16 v[2:5], v[204:207], v[188:191], v[2:5]
	v_mfma_f32_16x16x32_bf16 v[30:33], v[200:203], v[168:171], v[30:33]
	v_mfma_f32_16x16x32_bf16 v[26:29], v[208:211], v[168:171], v[26:29]
	v_mfma_f32_16x16x32_bf16 v[22:25], v[200:203], v[176:179], v[22:25]
	v_mfma_f32_16x16x32_bf16 v[18:21], v[208:211], v[176:179], v[18:21]
	v_mfma_f32_16x16x32_bf16 v[14:17], v[200:203], v[184:187], v[14:17]
	v_mfma_f32_16x16x32_bf16 v[10:13], v[208:211], v[184:187], v[10:13]
	v_mfma_f32_16x16x32_bf16 v[6:9], v[200:203], v[192:195], v[6:9]
	v_mfma_f32_16x16x32_bf16 v[2:5], v[208:211], v[192:195], v[2:5]
	s_barrier
	ds_read_b128 v[144:147], v130
	ds_read_b128 v[148:151], v130 offset:1024
	ds_read_b128 v[152:155], v130 offset:2048
	ds_read_b128 v[160:163], v130 offset:3072
	ds_read_b128 v[164:167], v143 offset:32768
	ds_read_b128 v[168:171], v143 offset:33792
	ds_read_b128 v[172:175], v142 offset:32768
	ds_read_b128 v[176:179], v142 offset:33792
	ds_read_b128 v[180:183], v141 offset:32768
	ds_read_b128 v[184:187], v141 offset:33792
	ds_read_b128 v[188:191], v140 offset:32768
	ds_read_b128 v[192:195], v140 offset:33792
	s_add_u32 s60, s62, 0x40100
	s_addc_u32 s61, s63, 0
	s_mov_b32 m0, s3
	s_nop 0
	global_load_lds_dwordx4 v139, s[60:61]
	s_mov_b32 m0, s14
	s_nop 0
	global_load_lds_dwordx4 v0, s[60:61]
	s_waitcnt lgkmcnt(8)
	s_barrier
	s_waitcnt lgkmcnt(0)
	s_waitcnt lgkmcnt(7)
	v_mfma_f32_16x16x32_bf16 v[126:129], v[144:147], v[164:167], v[126:129]
	v_mfma_f32_16x16x32_bf16 v[122:125], v[152:155], v[164:167], v[122:125]
	s_waitcnt lgkmcnt(5)
	v_mfma_f32_16x16x32_bf16 v[118:121], v[144:147], v[172:175], v[118:121]
	v_mfma_f32_16x16x32_bf16 v[114:117], v[152:155], v[172:175], v[114:117]
	s_waitcnt lgkmcnt(3)
	v_mfma_f32_16x16x32_bf16 v[110:113], v[144:147], v[180:183], v[110:113]
	v_mfma_f32_16x16x32_bf16 v[106:109], v[152:155], v[180:183], v[106:109]
	s_waitcnt lgkmcnt(1)
	v_mfma_f32_16x16x32_bf16 v[102:105], v[144:147], v[188:191], v[102:105]
	v_mfma_f32_16x16x32_bf16 v[98:101], v[152:155], v[188:191], v[98:101]
	v_mfma_f32_16x16x32_bf16 v[126:129], v[148:151], v[168:171], v[126:129]
	v_mfma_f32_16x16x32_bf16 v[122:125], v[160:163], v[168:171], v[122:125]
	v_mfma_f32_16x16x32_bf16 v[118:121], v[148:151], v[176:179], v[118:121]
	v_mfma_f32_16x16x32_bf16 v[114:117], v[160:163], v[176:179], v[114:117]
	v_mfma_f32_16x16x32_bf16 v[110:113], v[148:151], v[184:187], v[110:113]
	v_mfma_f32_16x16x32_bf16 v[106:109], v[160:163], v[184:187], v[106:109]
	s_waitcnt lgkmcnt(0)
	v_mfma_f32_16x16x32_bf16 v[102:105], v[148:151], v[192:195], v[102:105]
	v_mfma_f32_16x16x32_bf16 v[98:101], v[160:163], v[192:195], v[98:101]
	s_barrier
	ds_read_b128 v[196:199], v134
	ds_read_b128 v[200:203], v134 offset:1024
	ds_read_b128 v[204:207], v134 offset:2048
	ds_read_b128 v[208:211], v134 offset:3072
	s_add_u32 s60, s64, 0x180
	s_addc_u32 s61, s65, 0
	s_mov_b32 m0, s31
	s_nop 0
	global_load_lds_dwordx4 v139, s[60:61]
	s_mov_b32 m0, s34
	s_nop 0
	global_load_lds_dwordx4 v0, s[60:61]
	s_barrier
	s_waitcnt lgkmcnt(0)
	s_waitcnt lgkmcnt(3)
	v_mfma_f32_16x16x32_bf16 v[94:97], v[196:199], v[164:167], v[94:97]
	s_waitcnt lgkmcnt(1)
	v_mfma_f32_16x16x32_bf16 v[90:93], v[204:207], v[164:167], v[90:93]
	v_mfma_f32_16x16x32_bf16 v[86:89], v[196:199], v[172:175], v[86:89]
	v_mfma_f32_16x16x32_bf16 v[82:85], v[204:207], v[172:175], v[82:85]
	v_mfma_f32_16x16x32_bf16 v[78:81], v[196:199], v[180:183], v[78:81]
	v_mfma_f32_16x16x32_bf16 v[74:77], v[204:207], v[180:183], v[74:77]
	v_mfma_f32_16x16x32_bf16 v[70:73], v[196:199], v[188:191], v[70:73]
	v_mfma_f32_16x16x32_bf16 v[66:69], v[204:207], v[188:191], v[66:69]
	v_mfma_f32_16x16x32_bf16 v[94:97], v[200:203], v[168:171], v[94:97]
	s_waitcnt lgkmcnt(0)
	v_mfma_f32_16x16x32_bf16 v[90:93], v[208:211], v[168:171], v[90:93]
	v_mfma_f32_16x16x32_bf16 v[86:89], v[200:203], v[176:179], v[86:89]
	v_mfma_f32_16x16x32_bf16 v[82:85], v[208:211], v[176:179], v[82:85]
	v_mfma_f32_16x16x32_bf16 v[78:81], v[200:203], v[184:187], v[78:81]
	v_mfma_f32_16x16x32_bf16 v[74:77], v[208:211], v[184:187], v[74:77]
	v_mfma_f32_16x16x32_bf16 v[70:73], v[200:203], v[192:195], v[70:73]
	v_mfma_f32_16x16x32_bf16 v[66:69], v[208:211], v[192:195], v[66:69]
	s_barrier
	ds_read_b128 v[164:167], v143 offset:49152
	ds_read_b128 v[168:171], v143 offset:50176
	ds_read_b128 v[172:175], v142 offset:49152
	ds_read_b128 v[176:179], v142 offset:50176
	ds_read_b128 v[180:183], v141 offset:49152
	ds_read_b128 v[184:187], v141 offset:50176
	ds_read_b128 v[188:191], v140 offset:49152
	ds_read_b128 v[192:195], v140 offset:50176
	s_add_u32 s60, s66, 0x180
	s_addc_u32 s61, s67, 0
	s_mov_b32 m0, s35
	s_nop 0
	global_load_lds_dwordx4 v139, s[60:61]
	s_mov_b32 m0, s48
	s_nop 0
	global_load_lds_dwordx4 v0, s[60:61]
	s_barrier
; #define LDA(dst, b, h) for (int m = 0; m < 4; ++m) for (int k = 0; k < 2; ++k) \
;     dst[m][k] = *reinterpret_cast<const bf16x8*>((char*)SA(b, h) + lds_byte(wr * 64 + m * 16 + fr, k * 32 + fq * 8))
; #define LDB(dst, b, h) for (int n = 0; n < 2; ++n) for (int k = 0; k < 2; ++k) \
;     dst[n][k] = *reinterpret_cast<const bf16x8*>((char*)SB(b, h) + lds_byte(wc * 32 + n * 16 + fr, k * 32 + fq * 8))
; #define MMA(ai, bj, At_, Bt_) do { __builtin_amdgcn_s_setprio(1); \
;     for (int m = 0; m < 4; ++m) for (int n = 0; n < 2; ++n) for (int k = 0; k < 2; ++k) \
;       acc[ai][bj][m][n] = __builtin_amdgcn_mfma_f32_16x16x32_bf16(Bt_[n][k], At_[m][k], acc[ai][bj][m][n], 0, 0, 0); \
;     __builtin_amdgcn_s_setprio(0); } while (0)
; #define MMA_H(ai, bj, At_, Bt_) do { if (!HALFM) MMA(ai, bj, At_, Bt_); } while (0)
; #define WAIT_V(n) asm volatile("s_waitcnt vmcnt(" #n ")" ::: "memory")
; #define WAIT_L(n) asm volatile("s_waitcnt lgkmcnt(" #n ")" ::: "memory")
; #define BAR __builtin_amdgcn_s_barrier()
; #define SCHED __builtin_amdgcn_sched_barrier(0)
; template <int K, bool HALFM, class Epi>
; DI void gemm_tile(unsigned char* lds, const int tid, const u16* __restrict__ A, const u16* __restrict__ Bt, int brow, int bcol, Epi& epi,
;                   const bool prefetched, const bool has_next, const int nbrow, const int nbcol) {
;     ...
;     if (!HALFM) { LDA(At, 1, 1); } STAGE(SA(1, 0), A, brow, t + 3);
;     BAR; WAIT_L(0); MMA_H(1, 0, At, B0); BAR; SCHED;
;     STAGE(SB(1, 1), Bt, bcol + HALF, t + 3);
;     WAIT_V(6); BAR; MMA_H(1, 1, At, B1); BAR;
;   }
;   { LDB(B0, 0, 0); LDA(At, 0, 0); STAGE(SA(1, 1), A, brow + AH, nt - 1);
;     BAR; WAIT_L(0); MMA(0, 0, At, B0); BAR;
;     LDB(B1, 0, 1); BAR; WAIT_L(0); MMA(0, 1, At, B1); BAR;
	s_waitcnt lgkmcnt(0)
	s_waitcnt lgkmcnt(7)
	v_mfma_f32_16x16x32_bf16 v[62:65], v[144:147], v[164:167], v[62:65]
	v_mfma_f32_16x16x32_bf16 v[58:61], v[152:155], v[164:167], v[58:61]
	s_waitcnt lgkmcnt(5)
	v_mfma_f32_16x16x32_bf16 v[54:57], v[144:147], v[172:175], v[54:57]
	v_mfma_f32_16x16x32_bf16 v[50:53], v[152:155], v[172:175], v[50:53]
	s_waitcnt lgkmcnt(3)
	v_mfma_f32_16x16x32_bf16 v[46:49], v[144:147], v[180:183], v[46:49]
	v_mfma_f32_16x16x32_bf16 v[42:45], v[152:155], v[180:183], v[42:45]
	s_waitcnt lgkmcnt(1)
	v_mfma_f32_16x16x32_bf16 v[38:41], v[144:147], v[188:191], v[38:41]
	v_mfma_f32_16x16x32_bf16 v[34:37], v[152:155], v[188:191], v[34:37]
	v_mfma_f32_16x16x32_bf16 v[62:65], v[148:151], v[168:171], v[62:65]
	v_mfma_f32_16x16x32_bf16 v[58:61], v[160:163], v[168:171], v[58:61]
	v_mfma_f32_16x16x32_bf16 v[54:57], v[148:151], v[176:179], v[54:57]
	v_mfma_f32_16x16x32_bf16 v[50:53], v[160:163], v[176:179], v[50:53]
	v_mfma_f32_16x16x32_bf16 v[46:49], v[148:151], v[184:187], v[46:49]
	v_mfma_f32_16x16x32_bf16 v[42:45], v[160:163], v[184:187], v[42:45]
	s_waitcnt lgkmcnt(0)
	v_mfma_f32_16x16x32_bf16 v[38:41], v[148:151], v[192:195], v[38:41]
	v_mfma_f32_16x16x32_bf16 v[34:37], v[160:163], v[192:195], v[34:37]
	s_barrier
	s_add_u32 s60, s68, 0x180
	s_addc_u32 s61, s69, 0
	s_mov_b32 m0, s49
	s_nop 0
	global_load_lds_dwordx4 v139, s[60:61]
	s_mov_b32 m0, s50
	s_nop 0
	global_load_lds_dwordx4 v0, s[60:61]
	s_waitcnt vmcnt(6)
	s_barrier
	v_mfma_f32_16x16x32_bf16 v[30:33], v[196:199], v[164:167], v[30:33]
	v_mfma_f32_16x16x32_bf16 v[26:29], v[204:207], v[164:167], v[26:29]
	v_mfma_f32_16x16x32_bf16 v[22:25], v[196:199], v[172:175], v[22:25]
	v_mfma_f32_16x16x32_bf16 v[18:21], v[204:207], v[172:175], v[18:21]
	v_mfma_f32_16x16x32_bf16 v[14:17], v[196:199], v[180:183], v[14:17]
	v_mfma_f32_16x16x32_bf16 v[10:13], v[204:207], v[180:183], v[10:13]
	v_mfma_f32_16x16x32_bf16 v[6:9], v[196:199], v[188:191], v[6:9]
	v_mfma_f32_16x16x32_bf16 v[2:5], v[204:207], v[188:191], v[2:5]
	v_mfma_f32_16x16x32_bf16 v[30:33], v[200:203], v[168:171], v[30:33]
	v_mfma_f32_16x16x32_bf16 v[26:29], v[208:211], v[168:171], v[26:29]
	v_mfma_f32_16x16x32_bf16 v[22:25], v[200:203], v[176:179], v[22:25]
	v_mfma_f32_16x16x32_bf16 v[18:21], v[208:211], v[176:179], v[18:21]
	v_mfma_f32_16x16x32_bf16 v[14:17], v[200:203], v[184:187], v[14:17]
	v_mfma_f32_16x16x32_bf16 v[10:13], v[208:211], v[184:187], v[10:13]
	v_mfma_f32_16x16x32_bf16 v[6:9], v[200:203], v[192:195], v[6:9]
	v_mfma_f32_16x16x32_bf16 v[2:5], v[208:211], v[192:195], v[2:5]
	s_add_i32 s59, s59, 2
	s_add_u32 s0, s0, 0x100
	s_addc_u32 s1, s1, 0
	s_cmp_lt_u32 s59, 12
	s_barrier
	s_cbranch_scc1 .LBB0_996
	ds_read_b128 v[144:147], v132
	ds_read_b128 v[148:151], v132 offset:1024
	ds_read_b128 v[152:155], v132 offset:2048
	ds_read_b128 v[160:163], v132 offset:3072
	ds_read_b128 v[164:167], v143
	ds_read_b128 v[168:171], v143 offset:1024
	ds_read_b128 v[172:175], v142
	ds_read_b128 v[176:179], v142 offset:1024
	ds_read_b128 v[180:183], v141
	ds_read_b128 v[184:187], v141 offset:1024
	ds_read_b128 v[188:191], v140
	ds_read_b128 v[192:195], v140 offset:1024
	s_or_b32 s0, s2, 0x80
	s_ashr_i32 s1, s0, 31
	s_lshl_b64 s[0:1], s[0:1], 11
	v_readlane_b32 s10, v254, 59
	v_readlane_b32 s11, v254, 60
	s_add_u32 s0, s10, s0
	s_addc_u32 s1, s11, s1
	s_add_u32 s0, s0, 0x780
	s_addc_u32 s1, s1, 0
	s_mov_b32 m0, s7
	s_nop 0
	global_load_lds_dwordx4 v139, s[0:1]
	s_mov_b32 m0, s54
	s_nop 0
	global_load_lds_dwordx4 v0, s[0:1]
	s_barrier
	s_waitcnt lgkmcnt(0)
	s_waitcnt lgkmcnt(7)
	v_mfma_f32_16x16x32_bf16 v[126:129], v[144:147], v[164:167], v[126:129]
	v_mfma_f32_16x16x32_bf16 v[122:125], v[152:155], v[164:167], v[122:125]
	s_waitcnt lgkmcnt(5)
	v_mfma_f32_16x16x32_bf16 v[118:121], v[144:147], v[172:175], v[118:121]
	v_mfma_f32_16x16x32_bf16 v[114:117], v[152:155], v[172:175], v[114:117]
	s_waitcnt lgkmcnt(3)
	v_mfma_f32_16x16x32_bf16 v[110:113], v[144:147], v[180:183], v[110:113]
	s_waitcnt lgkmcnt(1)
	v_mfma_f32_16x16x32_bf16 v[102:105], v[144:147], v[188:191], v[102:105]
	v_mfma_f32_16x16x32_bf16 v[126:129], v[148:151], v[168:171], v[126:129]
	v_mfma_f32_16x16x32_bf16 v[122:125], v[160:163], v[168:171], v[122:125]
	v_mfma_f32_16x16x32_bf16 v[118:121], v[148:151], v[176:179], v[118:121]
	v_mfma_f32_16x16x32_bf16 v[114:117], v[160:163], v[176:179], v[114:117]
	v_mfma_f32_16x16x32_bf16 v[110:113], v[148:151], v[184:187], v[110:113]
	v_mfma_f32_16x16x32_bf16 v[106:109], v[152:155], v[180:183], v[106:109]
	s_waitcnt lgkmcnt(0)
	v_mfma_f32_16x16x32_bf16 v[102:105], v[148:151], v[192:195], v[102:105]
	v_mfma_f32_16x16x32_bf16 v[98:101], v[152:155], v[188:191], v[98:101]
	v_mfma_f32_16x16x32_bf16 v[196:199], v[160:163], v[184:187], v[106:109]
	v_mfma_f32_16x16x32_bf16 v[200:203], v[160:163], v[192:195], v[98:101]
	s_barrier
	s_nop 3
	ds_read_b128 v[98:101], v131
	ds_read_b128 v[106:109], v131 offset:1024
	ds_read_b128 v[204:207], v131 offset:2048
	ds_read_b128 v[208:211], v131 offset:3072
	s_barrier
	s_waitcnt lgkmcnt(0)
	s_waitcnt lgkmcnt(3)
	v_mfma_f32_16x16x32_bf16 v[94:97], v[98:101], v[164:167], v[94:97]
	v_mfma_f32_16x16x32_bf16 v[86:89], v[98:101], v[172:175], v[86:89]
	v_mfma_f32_16x16x32_bf16 v[78:81], v[98:101], v[180:183], v[78:81]
	s_waitcnt lgkmcnt(1)
	v_mfma_f32_16x16x32_bf16 v[74:77], v[204:207], v[180:183], v[74:77]
	v_mfma_f32_16x16x32_bf16 v[70:73], v[98:101], v[188:191], v[70:73]
	v_mfma_f32_16x16x32_bf16 v[66:69], v[204:207], v[188:191], v[66:69]
	v_mfma_f32_16x16x32_bf16 v[94:97], v[106:109], v[168:171], v[94:97]
	v_mfma_f32_16x16x32_bf16 v[90:93], v[204:207], v[164:167], v[90:93]
	v_mfma_f32_16x16x32_bf16 v[86:89], v[106:109], v[176:179], v[86:89]
	v_mfma_f32_16x16x32_bf16 v[82:85], v[204:207], v[172:175], v[82:85]
	v_mfma_f32_16x16x32_bf16 v[78:81], v[106:109], v[184:187], v[78:81]
	s_waitcnt lgkmcnt(0)
	v_mfma_f32_16x16x32_bf16 v[74:77], v[208:211], v[184:187], v[74:77]
	v_mfma_f32_16x16x32_bf16 v[70:73], v[106:109], v[192:195], v[70:73]
	v_mfma_f32_16x16x32_bf16 v[66:69], v[208:211], v[192:195], v[66:69]
	v_mfma_f32_16x16x32_bf16 v[164:167], v[208:211], v[168:171], v[90:93]
	v_mfma_f32_16x16x32_bf16 v[168:171], v[208:211], v[176:179], v[82:85]
	s_barrier
; #define LDA(dst, b, h) for (int m = 0; m < 4; ++m) for (int k = 0; k < 2; ++k) \
;     dst[m][k] = *reinterpret_cast<const bf16x8*>((char*)SA(b, h) + lds_byte(wr * 64 + m * 16 + fr, k * 32 + fq * 8))
; #define LDB(dst, b, h) for (int n = 0; n < 2; ++n) for (int k = 0; k < 2; ++k) \
;     dst[n][k] = *reinterpret_cast<const bf16x8*>((char*)SB(b, h) + lds_byte(wc * 32 + n * 16 + fr, k * 32 + fq * 8))
; #define MMA(ai, bj, At_, Bt_) do { __builtin_amdgcn_s_setprio(1); \
;     for (int m = 0; m < 4; ++m) for (int n = 0; n < 2; ++n) for (int k = 0; k < 2; ++k) \
;       acc[ai][bj][m][n] = __builtin_amdgcn_mfma_f32_16x16x32_bf16(Bt_[n][k], At_[m][k], acc[ai][bj][m][n], 0, 0, 0); \
;     __builtin_amdgcn_s_setprio(0); } while (0)
; #define MMA_H(ai, bj, At_, Bt_) do { if (!HALFM) MMA(ai, bj, At_, Bt_); } while (0)
; #define WAIT_V(n) asm volatile("s_waitcnt vmcnt(" #n ")" ::: "memory")
; #define WAIT_L(n) asm volatile("s_waitcnt lgkmcnt(" #n ")" ::: "memory")
; #define BAR __builtin_amdgcn_s_barrier()
; template <int K, bool HALFM, class Epi>
; DI void gemm_tile(unsigned char* lds, const int tid, const u16* __restrict__ A, const u16* __restrict__ Bt, int brow, int bcol, Epi& epi,
;                   const bool prefetched, const bool has_next, const int nbrow, const int nbcol) {
;     ...
;     LDB(B1, 0, 1); BAR; WAIT_L(0); MMA(0, 1, At, B1); BAR;
;     if (!HALFM) { LDA(At, 0, 1); } WAIT_V(4); BAR; WAIT_L(0); MMA_H(1, 0, At, B0); MMA_H(1, 1, At, B1); BAR; }
;   { LDB(B0, 1, 0); LDA(At, 1, 0); WAIT_V(2); BAR; WAIT_L(0); MMA(0, 0, At, B0); BAR;
;     LDB(B1, 1, 1); WAIT_V(0); BAR; WAIT_L(0); MMA(0, 1, At, B1); BAR;
	s_nop 0
	ds_read_b128 v[82:85], v143 offset:16384
	ds_read_b128 v[90:93], v143 offset:17408
	ds_read_b128 v[172:175], v142 offset:16384
	ds_read_b128 v[176:179], v142 offset:17408
	ds_read_b128 v[180:183], v141 offset:16384
	ds_read_b128 v[184:187], v141 offset:17408
	ds_read_b128 v[188:191], v140 offset:16384
	ds_read_b128 v[192:195], v140 offset:17408
	s_waitcnt vmcnt(4)
	s_barrier
	s_waitcnt lgkmcnt(0)
	s_waitcnt lgkmcnt(7)
	v_mfma_f32_16x16x32_bf16 v[62:65], v[144:147], v[82:85], v[62:65]
	v_mfma_f32_16x16x32_bf16 v[58:61], v[152:155], v[82:85], v[58:61]
	s_waitcnt lgkmcnt(5)
	v_mfma_f32_16x16x32_bf16 v[54:57], v[144:147], v[172:175], v[54:57]
	v_mfma_f32_16x16x32_bf16 v[50:53], v[152:155], v[172:175], v[50:53]
	s_waitcnt lgkmcnt(1)
	v_mfma_f32_16x16x32_bf16 v[38:41], v[144:147], v[188:191], v[38:41]
	v_mfma_f32_16x16x32_bf16 v[62:65], v[148:151], v[90:93], v[62:65]
	v_mfma_f32_16x16x32_bf16 v[58:61], v[160:163], v[90:93], v[58:61]
	v_mfma_f32_16x16x32_bf16 v[54:57], v[148:151], v[176:179], v[54:57]
	v_mfma_f32_16x16x32_bf16 v[50:53], v[160:163], v[176:179], v[50:53]
	v_mfma_f32_16x16x32_bf16 v[46:49], v[144:147], v[180:183], v[46:49]
	v_mfma_f32_16x16x32_bf16 v[42:45], v[152:155], v[180:183], v[42:45]
	s_waitcnt lgkmcnt(0)
	v_mfma_f32_16x16x32_bf16 v[38:41], v[148:151], v[192:195], v[38:41]
	v_mfma_f32_16x16x32_bf16 v[34:37], v[152:155], v[188:191], v[34:37]
	v_mfma_f32_16x16x32_bf16 v[212:215], v[148:151], v[184:187], v[46:49]
	v_mfma_f32_16x16x32_bf16 v[234:237], v[160:163], v[184:187], v[42:45]
	v_mfma_f32_16x16x32_bf16 v[34:37], v[160:163], v[192:195], v[34:37]
	v_mfma_f32_16x16x32_bf16 v[22:25], v[98:101], v[172:175], v[22:25]
	v_mfma_f32_16x16x32_bf16 v[14:17], v[98:101], v[180:183], v[14:17]
	v_mfma_f32_16x16x32_bf16 v[6:9], v[98:101], v[188:191], v[6:9]
	v_mfma_f32_16x16x32_bf16 v[30:33], v[98:101], v[82:85], v[30:33]
	v_mfma_f32_16x16x32_bf16 v[26:29], v[204:207], v[82:85], v[26:29]
	v_mfma_f32_16x16x32_bf16 v[22:25], v[106:109], v[176:179], v[22:25]
	v_mfma_f32_16x16x32_bf16 v[18:21], v[204:207], v[172:175], v[18:21]
	v_mfma_f32_16x16x32_bf16 v[14:17], v[106:109], v[184:187], v[14:17]
	v_mfma_f32_16x16x32_bf16 v[10:13], v[204:207], v[180:183], v[10:13]
	v_mfma_f32_16x16x32_bf16 v[6:9], v[106:109], v[192:195], v[6:9]
	v_mfma_f32_16x16x32_bf16 v[2:5], v[204:207], v[188:191], v[2:5]
	v_mfma_f32_16x16x32_bf16 v[30:33], v[106:109], v[90:93], v[30:33]
	v_mfma_f32_16x16x32_bf16 v[144:147], v[208:211], v[90:93], v[26:29]
	v_mfma_f32_16x16x32_bf16 v[148:151], v[208:211], v[176:179], v[18:21]
	v_mfma_f32_16x16x32_bf16 v[152:155], v[208:211], v[184:187], v[10:13]
	v_mfma_f32_16x16x32_bf16 v[160:163], v[208:211], v[192:195], v[2:5]
	s_barrier
	s_nop 0
	ds_read_b128 v[2:5], v130
	ds_read_b128 v[10:13], v130 offset:1024
	ds_read_b128 v[172:175], v130 offset:2048
	ds_read_b128 v[176:179], v130 offset:3072
	ds_read_b128 v[18:21], v143 offset:32768
	ds_read_b128 v[26:29], v143 offset:33792
	ds_read_b128 v[180:183], v142 offset:32768
	ds_read_b128 v[184:187], v142 offset:33792
	ds_read_b128 v[188:191], v141 offset:32768
	ds_read_b128 v[192:195], v141 offset:33792
	ds_read_b128 v[204:207], v140 offset:32768
	ds_read_b128 v[208:211], v140 offset:33792
	s_waitcnt vmcnt(2)
	s_barrier
	s_waitcnt lgkmcnt(0)
	s_waitcnt lgkmcnt(7)
	v_mfma_f32_16x16x32_bf16 v[46:49], v[172:175], v[18:21], v[122:125]
	s_waitcnt lgkmcnt(6)
	v_mfma_f32_16x16x32_bf16 v[130:133], v[176:179], v[26:29], v[46:49]
	s_waitcnt lgkmcnt(5)
	v_mfma_f32_16x16x32_bf16 v[46:49], v[2:5], v[180:183], v[118:121]
	s_waitcnt lgkmcnt(4)
	v_mfma_f32_16x16x32_bf16 v[122:125], v[10:13], v[184:187], v[46:49]
	v_mfma_f32_16x16x32_bf16 v[46:49], v[172:175], v[180:183], v[114:117]
	v_mfma_f32_16x16x32_bf16 v[114:117], v[176:179], v[184:187], v[46:49]
	s_waitcnt lgkmcnt(3)
	v_mfma_f32_16x16x32_bf16 v[46:49], v[2:5], v[188:191], v[110:113]
	s_waitcnt lgkmcnt(2)
	v_mfma_f32_16x16x32_bf16 v[106:109], v[10:13], v[192:195], v[46:49]
	v_mfma_f32_16x16x32_bf16 v[46:49], v[172:175], v[188:191], v[196:199]
	v_mfma_f32_16x16x32_bf16 v[98:101], v[176:179], v[192:195], v[46:49]
	s_waitcnt lgkmcnt(1)
	v_mfma_f32_16x16x32_bf16 v[46:49], v[2:5], v[204:207], v[102:105]
	v_mfma_f32_16x16x32_bf16 v[42:45], v[2:5], v[18:21], v[126:129]
	s_waitcnt lgkmcnt(0)
	v_mfma_f32_16x16x32_bf16 v[90:93], v[10:13], v[208:211], v[46:49]
	v_mfma_f32_16x16x32_bf16 v[46:49], v[172:175], v[204:207], v[200:203]
	v_mfma_f32_16x16x32_bf16 v[42:45], v[10:13], v[26:29], v[42:45]
	v_mfma_f32_16x16x32_bf16 v[82:85], v[176:179], v[208:211], v[46:49]
	s_barrier
	ds_read_b128 v[196:199], v134
	ds_read_b128 v[200:203], v134 offset:1024
	ds_read_b128 v[238:241], v134 offset:2048
	ds_read_b128 v[242:245], v134 offset:3072
	s_waitcnt vmcnt(0)
	s_barrier
	s_waitcnt lgkmcnt(0)
	s_waitcnt lgkmcnt(3)
	v_mfma_f32_16x16x32_bf16 v[46:49], v[196:199], v[18:21], v[94:97]
	s_waitcnt lgkmcnt(1)
	v_mfma_f32_16x16x32_bf16 v[18:21], v[238:241], v[18:21], v[164:167]
	s_waitcnt lgkmcnt(0)
	v_mfma_f32_16x16x32_bf16 v[134:137], v[242:245], v[26:29], v[18:21]
	v_mfma_f32_16x16x32_bf16 v[18:21], v[196:199], v[180:183], v[86:89]
	v_mfma_f32_16x16x32_bf16 v[126:129], v[200:203], v[184:187], v[18:21]
	v_mfma_f32_16x16x32_bf16 v[18:21], v[238:241], v[180:183], v[168:171]
	v_mfma_f32_16x16x32_bf16 v[118:121], v[242:245], v[184:187], v[18:21]
	v_mfma_f32_16x16x32_bf16 v[18:21], v[196:199], v[188:191], v[78:81]
	v_mfma_f32_16x16x32_bf16 v[110:113], v[200:203], v[192:195], v[18:21]
	v_mfma_f32_16x16x32_bf16 v[18:21], v[238:241], v[188:191], v[74:77]
	v_mfma_f32_16x16x32_bf16 v[102:105], v[242:245], v[192:195], v[18:21]
	v_mfma_f32_16x16x32_bf16 v[18:21], v[196:199], v[204:207], v[70:73]
	v_mfma_f32_16x16x32_bf16 v[94:97], v[200:203], v[208:211], v[18:21]
	v_mfma_f32_16x16x32_bf16 v[18:21], v[238:241], v[204:207], v[66:69]
	v_mfma_f32_16x16x32_bf16 v[46:49], v[200:203], v[26:29], v[46:49]
	v_mfma_f32_16x16x32_bf16 v[86:89], v[242:245], v[208:211], v[18:21]
	s_barrier
; #define LDA(dst, b, h) for (int m = 0; m < 4; ++m) for (int k = 0; k < 2; ++k) \
;     dst[m][k] = *reinterpret_cast<const bf16x8*>((char*)SA(b, h) + lds_byte(wr * 64 + m * 16 + fr, k * 32 + fq * 8))
; #define MMA_H(ai, bj, At_, Bt_) do { if (!HALFM) MMA(ai, bj, At_, Bt_); } while (0)
; #define WAIT_L(n) asm volatile("s_waitcnt lgkmcnt(" #n ")" ::: "memory")
; #define BAR __builtin_amdgcn_s_barrier()
; template <int K, bool HALFM, class Epi>
; DI void gemm_tile(unsigned char* lds, const int tid, const u16* __restrict__ A, const u16* __restrict__ Bt, int brow, int bcol, Epi& epi,
;                   const bool prefetched, const bool has_next, const int nbrow, const int nbcol) {
;     ...
;     if (!HALFM) { LDA(At, 1, 1); } BAR; WAIT_L(0); MMA_H(1, 0, At, B0); MMA_H(1, 1, At, B1); BAR; }
;   if (wr == 0) BAR;
;   if (has_next) {
;     STAGE(SB(0, 0), Bt, nbcol, 0); STAGE(SA(0, 0), A, nbrow, 0);
;     STAGE(SB(0, 1), Bt, nbcol + HALF, 0); STAGE(SA(0, 1), A, nbrow + AH, 0);
;     STAGE(SB(1, 0), Bt, nbcol, 1); STAGE(SA(1, 0), A, nbrow, 1); STAGE(SB(1, 1), Bt, nbcol + HALF, 1);
;   }
;   DI void operator()(f32x4 (&acc)[2][2][4][2], int brow, int bcol, int wr, int wc, int fr, int fq, const int nai) const {
;     const int bi = brow < M_LAT ? (brow >> 11) : 8;
;     const float* swr = sw + bi * SW_LD + bcol + wc * 32 + fq * 4;
;     const float4 sa0 = ld4(swr), sa1 = ld4(swr + 16), sb0 = ld4(swr + 128), sb1 = ld4(swr + 144);
	ds_read_b128 v[70:73], v143 offset:49152
	ds_read_b128 v[164:167], v143 offset:50176
	ds_read_b128 v[168:171], v142 offset:49152
	ds_read_b128 v[180:183], v142 offset:50176
	ds_read_b128 v[184:187], v141 offset:49152
	ds_read_b128 v[188:191], v141 offset:50176
	ds_read_b128 v[192:195], v140 offset:49152
	ds_read_b128 v[140:143], v140 offset:50176
	s_barrier
	s_waitcnt lgkmcnt(0)
	s_waitcnt lgkmcnt(7)
	v_mfma_f32_16x16x32_bf16 v[18:21], v[2:5], v[70:73], v[62:65]
	s_waitcnt lgkmcnt(6)
	v_mfma_f32_16x16x32_bf16 v[74:77], v[10:13], v[164:167], v[18:21]
	v_mfma_f32_16x16x32_bf16 v[18:21], v[172:175], v[70:73], v[58:61]
	v_mfma_f32_16x16x32_bf16 v[66:69], v[176:179], v[164:167], v[18:21]
	s_waitcnt lgkmcnt(5)
	v_mfma_f32_16x16x32_bf16 v[18:21], v[2:5], v[168:171], v[54:57]
	s_waitcnt lgkmcnt(4)
	v_mfma_f32_16x16x32_bf16 v[58:61], v[10:13], v[180:183], v[18:21]
	v_mfma_f32_16x16x32_bf16 v[18:21], v[172:175], v[168:171], v[50:53]
	v_mfma_f32_16x16x32_bf16 v[50:53], v[176:179], v[180:183], v[18:21]
	s_waitcnt lgkmcnt(3)
	v_mfma_f32_16x16x32_bf16 v[18:21], v[2:5], v[184:187], v[212:215]
	s_waitcnt lgkmcnt(1)
	v_mfma_f32_16x16x32_bf16 v[2:5], v[2:5], v[192:195], v[38:41]
	v_mfma_f32_16x16x32_bf16 v[26:29], v[10:13], v[188:191], v[18:21]
	v_mfma_f32_16x16x32_bf16 v[18:21], v[172:175], v[184:187], v[234:237]
	s_waitcnt lgkmcnt(0)
	v_mfma_f32_16x16x32_bf16 v[10:13], v[10:13], v[140:143], v[2:5]
	v_mfma_f32_16x16x32_bf16 v[2:5], v[172:175], v[192:195], v[34:37]
	v_mfma_f32_16x16x32_bf16 v[18:21], v[176:179], v[188:191], v[18:21]
	v_mfma_f32_16x16x32_bf16 v[2:5], v[176:179], v[140:143], v[2:5]
	v_mfma_f32_16x16x32_bf16 v[22:25], v[196:199], v[168:171], v[22:25]
	v_mfma_f32_16x16x32_bf16 v[14:17], v[196:199], v[184:187], v[14:17]
	v_mfma_f32_16x16x32_bf16 v[30:33], v[196:199], v[70:73], v[30:33]
	v_mfma_f32_16x16x32_bf16 v[62:65], v[200:203], v[180:183], v[22:25]
	v_mfma_f32_16x16x32_bf16 v[22:25], v[238:241], v[168:171], v[148:151]
	v_mfma_f32_16x16x32_bf16 v[38:41], v[200:203], v[188:191], v[14:17]
	v_mfma_f32_16x16x32_bf16 v[14:17], v[238:241], v[184:187], v[152:155]
	v_mfma_f32_16x16x32_bf16 v[6:9], v[196:199], v[192:195], v[6:9]
	v_mfma_f32_16x16x32_bf16 v[78:81], v[200:203], v[164:167], v[30:33]
	v_mfma_f32_16x16x32_bf16 v[30:33], v[238:241], v[70:73], v[144:147]
	v_mfma_f32_16x16x32_bf16 v[54:57], v[242:245], v[180:183], v[22:25]
	v_mfma_f32_16x16x32_bf16 v[22:25], v[242:245], v[188:191], v[14:17]
	v_mfma_f32_16x16x32_bf16 v[14:17], v[200:203], v[140:143], v[6:9]
	v_mfma_f32_16x16x32_bf16 v[6:9], v[238:241], v[192:195], v[160:163]
	v_mfma_f32_16x16x32_bf16 v[70:73], v[242:245], v[164:167], v[30:33]
	v_mfma_f32_16x16x32_bf16 v[6:9], v[242:245], v[140:143], v[6:9]
	s_movk_i32 s0, 0x100
	v_cmp_gt_u32_e32 vcc, s0, v138
	s_barrier
	s_and_saveexec_b64 s[0:1], vcc
	s_cbranch_execz .LBB0_999
	s_barrier
.LBB0_999:
	s_setprio 0
	s_or_b64 exec, exec, s[0:1]
	s_min_i32 s100, s2, 0x4000
	s_ashr_i32 s100, s100, 11
	s_mul_hi_i32 s101, s100, 0x5800
	s_mulk_i32 s100, 0x5800
	s_add_u32 s100, s16, s100
	s_addc_u32 s101, s17, s101
	s_lshl_b64 vcc, s[8:9], 2
	s_add_u32 s100, s100, vcc_lo
	s_addc_u32 s101, s101, vcc_hi
	v_lshrrev_b32_e32 v152, 1, v138
	v_and_b32_e32 v152, 0x60, v152
	v_lshlrev_b32_e32 v152, 2, v152
	v_and_b32_e32 v153, 48, v138
	v_add_u32_e32 v152, v152, v153
	global_load_dwordx4 v[160:163], v152, s[100:101]
	global_load_dwordx4 v[164:167], v152, s[100:101] offset:512
	global_load_dwordx4 v[168:171], v152, s[100:101] offset:64
	global_load_dwordx4 v[172:175], v152, s[100:101] offset:576
	s_andn2_b64 vcc, exec, s[46:47]
	s_mov_b32 s54, 0x800000
	s_movk_i32 s62, 0x21ff
	s_movk_i32 s63, 0x2000
	s_cbranch_vccnz .Lsw_nonext
	s_ashr_i32 s7, s6, 31
	s_lshl_b64 s[0:1], s[6:7], 11
	s_add_u32 s0, s18, s0
	s_addc_u32 s1, s19, s1
	s_mov_b32 m0, s5
	s_nop 0
	global_load_lds_dwordx4 v139, s[0:1]
	s_mov_b32 m0, s53
	s_nop 0
	global_load_lds_dwordx4 v0, s[0:1]
	s_ashr_i32 s5, s4, 31
	s_lshl_b64 s[10:11], s[4:5], 11
	v_readlane_b32 s12, v254, 59
	v_readlane_b32 s13, v254, 60
	s_add_u32 s10, s12, s10
	s_addc_u32 s11, s13, s11
	s_bitset1_b32 s6, 7
	s_ashr_i32 s7, s6, 31
	s_lshl_b64 s[6:7], s[6:7], 11
	s_add_u32 s6, s18, s6
	s_addc_u32 s7, s19, s7
	s_bitset1_b32 s4, 7
	s_ashr_i32 s5, s4, 31
	s_lshl_b64 s[4:5], s[4:5], 11
	s_add_u32 s4, s12, s4
	s_mov_b32 m0, s21
	s_nop 0
	global_load_lds_dwordx4 v139, s[10:11]
	s_mov_b32 m0, s52
	s_nop 0
	global_load_lds_dwordx4 v0, s[10:11]
	s_addc_u32 s5, s13, s5
	s_mov_b32 m0, s15
	s_nop 0
	global_load_lds_dwordx4 v139, s[6:7]
	s_mov_b32 m0, s51
	s_nop 0
	global_load_lds_dwordx4 v0, s[6:7]
	s_add_u32 s0, s0, 0x80
	s_mov_b32 m0, s3
	s_nop 0
	global_load_lds_dwordx4 v139, s[4:5]
	s_mov_b32 m0, s14
	s_nop 0
	global_load_lds_dwordx4 v0, s[4:5]
	s_addc_u32 s1, s1, 0
	s_mov_b32 m0, s31
	s_nop 0
	global_load_lds_dwordx4 v139, s[0:1]
	s_mov_b32 m0, s34
	s_nop 0
	global_load_lds_dwordx4 v0, s[0:1]
	s_add_u32 s0, s10, 0x80
	s_addc_u32 s1, s11, 0
	s_mov_b32 m0, s35
	s_nop 0
	global_load_lds_dwordx4 v139, s[0:1]
	s_mov_b32 m0, s48
	s_nop 0
	global_load_lds_dwordx4 v0, s[0:1]
	s_add_u32 s0, s6, 0x80
	s_addc_u32 s1, s7, 0
	s_mov_b32 m0, s49
	s_nop 0
	global_load_lds_dwordx4 v139, s[0:1]
	s_mov_b32 m0, s50
	s_nop 0
	global_load_lds_dwordx4 v0, s[0:1]
	s_waitcnt vmcnt(14)
	s_branch .LBB0_969
